# P4 loads without nt hint
# speedup vs baseline: 1.0129x; 1.0129x over previous
; DI void phase_fixup(const Params& p) {
;     ...
;     for (int it = blockIdx.x; it < 512; it += gridDim.x) {
;         const int c = it >> 2, rq = it & 3;
;         float cf[8], cb[8];
;         { const f32x4 a0 = *(const f32x4*)(CAR + (size_t)c * 2048 + ch), a1 = *(const f32x4*)(CAR + (size_t)c * 2048 + ch + 4);
;           const f32x4 b0 = *(const f32x4*)(CAR + (size_t)(128 + c) * 2048 + ch), b1 = *(const f32x4*)(CAR + (size_t)(128 + c) * 2048 + ch + 4);
; #pragma unroll
;           for (int i = 0; i < 4; ++i) { cf[i] = a0[i] * (1.f / 255.f); cf[4 + i] = a1[i] * (1.f / 255.f); cb[i] = b0[i] * (1.f / 255.f); cb[4 + i] = b1[i] * (1.f / 255.f); } }
; #pragma unroll 8
;         for (int i = 0; i < 16; ++i) {
;             const size_t off = (size_t)(c * 128 + rq * 32 + 2 * i + r2) * 2048 + ch;
;             const u32x4 g = __builtin_nontemporal_load((const u32x4*)(ZG + off)), h = __builtin_nontemporal_load((const u32x4*)(HLp + off)), pp = __builtin_nontemporal_load((const u32x4*)(PPp + off));
.LBB0_377:
	s_ashr_i32 s20, s17, 2
	s_ashr_i32 s21, s20, 31
	s_lshl_b64 s[18:19], s[20:21], 13
	v_lshl_add_u64 v[2:3], v[0:1], 0, s[18:19]
	v_add_co_u32_e32 v12, vcc, 0x100000, v2
	global_load_dwordx4 v[14:17], v[2:3], off offset:16
	global_load_dwordx4 v[18:21], v[2:3], off
	v_addc_co_u32_e32 v13, vcc, 0, v3, vcc
	v_lshl_add_u64 v[10:11], v[2:3], 0, s[6:7]
	global_load_dwordx4 v[2:5], v[12:13], off
	global_load_dwordx4 v[6:9], v[10:11], off offset:16
	s_and_b32 s19, s15, 0x60
	v_lshl_or_b32 v26, s20, 7, v50
	s_mov_b32 s18, 0
	v_or_b32_e32 v52, s19, v26
	v_lshl_or_b32 v22, v52, 12, v51
	v_mov_b32_e32 v70, v22
	s_mov_b32 s40, 0xbfb8aa3b
	global_load_dwordx4 v[28:31], v70, s[10:11]
	global_load_dwordx4 v[32:35], v70, s[4:5]
	global_load_dwordx4 v[36:39], v70, s[12:13]
	s_waitcnt vmcnt(3)
	v_pk_mul_f32 v[18:19], v[18:19], s[14:15] op_sel_hi:[1,0]
	v_pk_mul_f32 v[20:21], v[20:21], s[14:15] op_sel_hi:[1,0]
	v_pk_mul_f32 v[14:15], v[14:15], s[14:15] op_sel_hi:[1,0]
	v_pk_mul_f32 v[16:17], v[16:17], s[14:15] op_sel_hi:[1,0]
	v_pk_mul_f32 v[2:3], v[2:3], s[14:15] op_sel_hi:[1,0]
	v_pk_mul_f32 v[4:5], v[4:5], s[14:15] op_sel_hi:[1,0]
	v_pk_mul_f32 v[6:7], v[6:7], s[14:15] op_sel_hi:[1,0]
	v_pk_mul_f32 v[8:9], v[8:9], s[14:15] op_sel_hi:[1,0]
	s_waitcnt vmcnt(0)
; DI unsigned cvtpk(float lo, float hi) { unsigned r; asm volatile("v_cvt_pk_bf16_f32 %0, %1, %2" : "=v"(r) : "v"(lo), "v"(hi)); return r; }
; DI float bflo(unsigned w) { return __uint_as_float(w << 16); }
; DI float bfhi(unsigned w) { return __uint_as_float(w & 0xffff0000u); }
; DI float sigm(float x) { return rcpf_(1.f + ex2(-x * LOG2E)); }
; DI float ub(unsigned w, int i) { return (float)((w >> (8 * i)) & 0xffu); }
; DI void phase_fixup(const Params& p) {
;     ...
;         for (int i = 0; i < 16; ++i) {
;             const size_t off = (size_t)(c * 128 + rq * 32 + 2 * i + r2) * 2048 + ch;
;             const u32x4 g = __builtin_nontemporal_load((const u32x4*)(ZG + off)), h = __builtin_nontemporal_load((const u32x4*)(HLp + off)), pp = __builtin_nontemporal_load((const u32x4*)(PPp + off));
;             u32x4 o;
; #pragma unroll
;             for (int k = 0; k < 4; ++k) {
;                 const float g0 = bflo(g[k]), g1 = bfhi(g[k]);
;                 const float y0 = (bflo(h[k]) + ub(pp[k], 0) * cf[2 * k] + ub(pp[k], 1) * cb[2 * k]) * g0 * sigm(g0);
;                 const float y1 = (bfhi(h[k]) + ub(pp[k], 2) * cf[2 * k + 1] + ub(pp[k], 3) * cb[2 * k + 1]) * g1 * sigm(g1);
;                 o[k] = cvtpk(y0, y1);
;             }
;             *(u32x4*)(ZG + off) = o;
;         }
.Lp4_row_loop:
	s_add_i32 s42, s18, 1
	s_min_u32 s42, s42, 15
	s_lshl_b32 s42, s42, 13
	v_add_u32_e32 v71, s42, v22
	global_load_dwordx4 v[54:57], v71, s[10:11]
	global_load_dwordx4 v[58:61], v71, s[4:5]
	global_load_dwordx4 v[62:65], v71, s[12:13]
	s_waitcnt vmcnt(4)
	v_lshlrev_b32_e32 v72, 16, v28
	v_and_b32_e32 v73, 0xffff0000, v28
	v_lshlrev_b32_e32 v80, 16, v32
	v_and_b32_e32 v81, 0xffff0000, v32
	v_cvt_f32_ubyte0_e32 v88, v36
	v_cvt_f32_ubyte2_e32 v89, v36
	v_cvt_f32_ubyte1_e32 v96, v36
	v_cvt_f32_ubyte3_e32 v97, v36
	v_lshlrev_b32_e32 v74, 16, v29
	v_and_b32_e32 v75, 0xffff0000, v29
	v_lshlrev_b32_e32 v82, 16, v33
	v_and_b32_e32 v83, 0xffff0000, v33
	v_cvt_f32_ubyte0_e32 v90, v37
	v_cvt_f32_ubyte2_e32 v91, v37
	v_cvt_f32_ubyte1_e32 v98, v37
	v_cvt_f32_ubyte3_e32 v99, v37
	v_lshlrev_b32_e32 v76, 16, v30
	v_and_b32_e32 v77, 0xffff0000, v30
	v_lshlrev_b32_e32 v84, 16, v34
	v_and_b32_e32 v85, 0xffff0000, v34
	v_cvt_f32_ubyte0_e32 v92, v38
	v_cvt_f32_ubyte2_e32 v93, v38
	v_cvt_f32_ubyte1_e32 v100, v38
	v_cvt_f32_ubyte3_e32 v101, v38
	v_lshlrev_b32_e32 v78, 16, v31
	v_and_b32_e32 v79, 0xffff0000, v31
	v_lshlrev_b32_e32 v86, 16, v35
	v_and_b32_e32 v87, 0xffff0000, v35
	v_cvt_f32_ubyte0_e32 v94, v39
	v_cvt_f32_ubyte2_e32 v95, v39
	v_cvt_f32_ubyte1_e32 v102, v39
	v_cvt_f32_ubyte3_e32 v103, v39
	v_pk_mul_f32 v[104:105], v[72:73], s[40:41] op_sel_hi:[1,0]
	v_pk_mul_f32 v[106:107], v[74:75], s[40:41] op_sel_hi:[1,0]
	v_pk_mul_f32 v[108:109], v[76:77], s[40:41] op_sel_hi:[1,0]
	v_pk_mul_f32 v[110:111], v[78:79], s[40:41] op_sel_hi:[1,0]
	v_pk_fma_f32 v[80:81], v[88:89], v[18:19], v[80:81]
	v_pk_fma_f32 v[82:83], v[90:91], v[20:21], v[82:83]
	v_pk_fma_f32 v[84:85], v[92:93], v[14:15], v[84:85]
	v_pk_fma_f32 v[86:87], v[94:95], v[16:17], v[86:87]
	v_exp_f32_e32 v104, v104
	v_exp_f32_e32 v105, v105
	v_exp_f32_e32 v106, v106
	v_exp_f32_e32 v107, v107
	v_exp_f32_e32 v108, v108
	v_exp_f32_e32 v109, v109
	v_exp_f32_e32 v110, v110
	v_exp_f32_e32 v111, v111
	v_pk_fma_f32 v[80:81], v[96:97], v[2:3], v[80:81]
	v_pk_fma_f32 v[82:83], v[98:99], v[4:5], v[82:83]
	v_pk_fma_f32 v[84:85], v[100:101], v[6:7], v[84:85]
	v_pk_fma_f32 v[86:87], v[102:103], v[8:9], v[86:87]
	v_pk_add_f32 v[104:105], v[104:105], 1.0 op_sel_hi:[1,0]
	v_pk_add_f32 v[106:107], v[106:107], 1.0 op_sel_hi:[1,0]
	v_pk_add_f32 v[108:109], v[108:109], 1.0 op_sel_hi:[1,0]
	v_pk_add_f32 v[110:111], v[110:111], 1.0 op_sel_hi:[1,0]
	v_rcp_f32_e32 v104, v104
	v_rcp_f32_e32 v105, v105
	v_rcp_f32_e32 v106, v106
	v_rcp_f32_e32 v107, v107
	v_rcp_f32_e32 v108, v108
	v_rcp_f32_e32 v109, v109
	v_rcp_f32_e32 v110, v110
	v_rcp_f32_e32 v111, v111
	v_pk_mul_f32 v[80:81], v[80:81], v[72:73]
	v_pk_mul_f32 v[82:83], v[82:83], v[74:75]
	v_pk_mul_f32 v[84:85], v[84:85], v[76:77]
	v_pk_mul_f32 v[86:87], v[86:87], v[78:79]
	v_pk_mul_f32 v[80:81], v[104:105], v[80:81]
	v_pk_mul_f32 v[82:83], v[106:107], v[82:83]
	v_pk_mul_f32 v[84:85], v[108:109], v[84:85]
	v_pk_mul_f32 v[86:87], v[110:111], v[86:87]
	v_cvt_pk_bf16_f32 v24, v80, v81
	v_cvt_pk_bf16_f32 v25, v82, v83
	v_cvt_pk_bf16_f32 v26, v84, v85
	v_cvt_pk_bf16_f32 v27, v86, v87
	global_store_dwordx4 v70, v[24:27], s[10:11]
	s_add_i32 s42, s18, 2
	s_min_u32 s42, s42, 15
	s_lshl_b32 s42, s42, 13
	v_add_u32_e32 v70, s42, v22
	global_load_dwordx4 v[28:31], v70, s[10:11]
	global_load_dwordx4 v[32:35], v70, s[4:5]
	global_load_dwordx4 v[36:39], v70, s[12:13]
	s_waitcnt vmcnt(4)
	v_lshlrev_b32_e32 v72, 16, v54
	v_and_b32_e32 v73, 0xffff0000, v54
	v_lshlrev_b32_e32 v80, 16, v58
	v_and_b32_e32 v81, 0xffff0000, v58
	v_cvt_f32_ubyte0_e32 v88, v62
	v_cvt_f32_ubyte2_e32 v89, v62
	v_cvt_f32_ubyte1_e32 v96, v62
	v_cvt_f32_ubyte3_e32 v97, v62
	v_lshlrev_b32_e32 v74, 16, v55
	v_and_b32_e32 v75, 0xffff0000, v55
	v_lshlrev_b32_e32 v82, 16, v59
	v_and_b32_e32 v83, 0xffff0000, v59
	v_cvt_f32_ubyte0_e32 v90, v63
	v_cvt_f32_ubyte2_e32 v91, v63
	v_cvt_f32_ubyte1_e32 v98, v63
	v_cvt_f32_ubyte3_e32 v99, v63
	v_lshlrev_b32_e32 v76, 16, v56
	v_and_b32_e32 v77, 0xffff0000, v56
	v_lshlrev_b32_e32 v84, 16, v60
	v_and_b32_e32 v85, 0xffff0000, v60
	v_cvt_f32_ubyte0_e32 v92, v64
	v_cvt_f32_ubyte2_e32 v93, v64
	v_cvt_f32_ubyte1_e32 v100, v64
	v_cvt_f32_ubyte3_e32 v101, v64
	v_lshlrev_b32_e32 v78, 16, v57
	v_and_b32_e32 v79, 0xffff0000, v57
	v_lshlrev_b32_e32 v86, 16, v61
	v_and_b32_e32 v87, 0xffff0000, v61
	v_cvt_f32_ubyte0_e32 v94, v65
	v_cvt_f32_ubyte2_e32 v95, v65
	v_cvt_f32_ubyte1_e32 v102, v65
	v_cvt_f32_ubyte3_e32 v103, v65
	v_pk_mul_f32 v[104:105], v[72:73], s[40:41] op_sel_hi:[1,0]
	v_pk_mul_f32 v[106:107], v[74:75], s[40:41] op_sel_hi:[1,0]
	v_pk_mul_f32 v[108:109], v[76:77], s[40:41] op_sel_hi:[1,0]
	v_pk_mul_f32 v[110:111], v[78:79], s[40:41] op_sel_hi:[1,0]
	v_pk_fma_f32 v[80:81], v[88:89], v[18:19], v[80:81]
	v_pk_fma_f32 v[82:83], v[90:91], v[20:21], v[82:83]
	v_pk_fma_f32 v[84:85], v[92:93], v[14:15], v[84:85]
	v_pk_fma_f32 v[86:87], v[94:95], v[16:17], v[86:87]
	v_exp_f32_e32 v104, v104
	v_exp_f32_e32 v105, v105
	v_exp_f32_e32 v106, v106
	v_exp_f32_e32 v107, v107
	v_exp_f32_e32 v108, v108
	v_exp_f32_e32 v109, v109
	v_exp_f32_e32 v110, v110
	v_exp_f32_e32 v111, v111
	v_pk_fma_f32 v[80:81], v[96:97], v[2:3], v[80:81]
	v_pk_fma_f32 v[82:83], v[98:99], v[4:5], v[82:83]
	v_pk_fma_f32 v[84:85], v[100:101], v[6:7], v[84:85]
	v_pk_fma_f32 v[86:87], v[102:103], v[8:9], v[86:87]
	v_pk_add_f32 v[104:105], v[104:105], 1.0 op_sel_hi:[1,0]
	v_pk_add_f32 v[106:107], v[106:107], 1.0 op_sel_hi:[1,0]
	v_pk_add_f32 v[108:109], v[108:109], 1.0 op_sel_hi:[1,0]
	v_pk_add_f32 v[110:111], v[110:111], 1.0 op_sel_hi:[1,0]
	v_rcp_f32_e32 v104, v104
	v_rcp_f32_e32 v105, v105
	v_rcp_f32_e32 v106, v106
	v_rcp_f32_e32 v107, v107
	v_rcp_f32_e32 v108, v108
	v_rcp_f32_e32 v109, v109
	v_rcp_f32_e32 v110, v110
	v_rcp_f32_e32 v111, v111
	v_pk_mul_f32 v[80:81], v[80:81], v[72:73]
	v_pk_mul_f32 v[82:83], v[82:83], v[74:75]
	v_pk_mul_f32 v[84:85], v[84:85], v[76:77]
	v_pk_mul_f32 v[86:87], v[86:87], v[78:79]
	v_pk_mul_f32 v[80:81], v[104:105], v[80:81]
	v_pk_mul_f32 v[82:83], v[106:107], v[82:83]
	v_pk_mul_f32 v[84:85], v[108:109], v[84:85]
	v_pk_mul_f32 v[86:87], v[110:111], v[86:87]
	v_cvt_pk_bf16_f32 v66, v80, v81
	v_cvt_pk_bf16_f32 v67, v82, v83
	v_cvt_pk_bf16_f32 v68, v84, v85
	v_cvt_pk_bf16_f32 v69, v86, v87
	global_store_dwordx4 v71, v[66:69], s[10:11]
	s_add_i32 s18, s18, 2
	s_cmp_lt_u32 s18, 16
	s_cbranch_scc1 .Lp4_row_loop
	s_add_i32 s17, s17, s24
	s_add_i32 s15, s15, s16
	s_cmpk_gt_i32 s17, 0x1ff
	s_cbranch_scc0 .LBB0_377
	s_load_dwordx2 s[4:5], s[0:1], 0xc8
	s_waitcnt lgkmcnt(0)
	v_mov_b64_e32 v[0:1], s[4:5]
